# pipelined residual-add epilogues (mix, mem_o, ffn_out) and batched gate loads in merge
# speedup vs baseline: 1.0460x; 1.0077x over previous
.LBB0_1183:
	s_mov_b32 s25, s0
	s_mul_hi_i32 s26, s25, 0x230000
	s_mul_i32 s25, s25, 0x230000
	s_add_u32 s25, s92, s25
	s_addc_u32 s26, s93, s26
	s_lshl_b32 s27, s1, 11
	s_add_u32 s25, s25, s27
	s_addc_u32 s26, s26, 0
	s_add_u32 s25, s25, s64
	v_mov_b32_e32 v64, v166
	s_addc_u32 s27, s26, s65
	s_add_u32 s26, s25, 0x23606f00
	v_and_b32_e32 v66, 0xc0, v64
	v_and_b32_e32 v67, 15, v64
	v_lshrrev_b32_e32 v64, 2, v64
	s_mov_b32 s25, 0xffffc0
	v_and_or_b32 v67, v64, s25, v67
	v_and_b32_e32 v64, 12, v64
	v_mul_u32_u24_e32 v67, 0x2300, v67
	s_addc_u32 s27, s27, 0
	v_or3_b32 v64, v64, v66, v67
	v_lshl_add_u64 v[246:247], v[64:65], 1, s[26:27]
	v_add_u32_e32 v248, 0x23000, v64
	v_mov_b32_e32 v249, 0
	v_lshl_add_u64 v[248:249], v[248:249], 1, s[26:27]
	v_add_u32_e32 v250, 0x46000, v64
	v_mov_b32_e32 v251, 0
	v_lshl_add_u64 v[250:251], v[250:251], 1, s[26:27]
	v_add_u32_e32 v252, 0x69000, v64
	v_mov_b32_e32 v253, 0
	v_lshl_add_u64 v[252:253], v[252:253], 1, s[26:27]
	global_load_dwordx2 v[66:67], v[246:247], off
	global_load_dwordx2 v[68:69], v[246:247], off offset:32
	global_load_dwordx2 v[70:71], v[246:247], off offset:64
	global_load_dwordx2 v[72:73], v[246:247], off offset:96
	global_load_dwordx2 v[74:75], v[248:249], off
	global_load_dwordx2 v[76:77], v[248:249], off offset:32
	global_load_dwordx2 v[78:79], v[248:249], off offset:64
	global_load_dwordx2 v[80:81], v[248:249], off offset:96
	global_load_dwordx2 v[82:83], v[250:251], off
	global_load_dwordx2 v[84:85], v[250:251], off offset:32
	global_load_dwordx2 v[86:87], v[250:251], off offset:64
	global_load_dwordx2 v[88:89], v[250:251], off offset:96
	global_load_dwordx2 v[200:201], v[252:253], off
	global_load_dwordx2 v[202:203], v[252:253], off offset:32
	global_load_dwordx2 v[204:205], v[252:253], off offset:64
	global_load_dwordx2 v[206:207], v[252:253], off offset:96
	s_waitcnt vmcnt(15)
	v_lshlrev_b32_e32 v254, 16, v66
	v_and_b32_e32 v255, 0xffff0000, v66
	v_pk_fma_f32 v[144:145], v[60:61], v[254:255], v[144:145]
	v_lshlrev_b32_e32 v66, 16, v67
	v_and_b32_e32 v67, 0xffff0000, v67
	v_pk_fma_f32 v[152:153], v[62:63], v[66:67], v[152:153]
	s_waitcnt vmcnt(14)
	v_lshlrev_b32_e32 v254, 16, v68
	v_and_b32_e32 v255, 0xffff0000, v68
	v_pk_fma_f32 v[146:147], v[56:57], v[254:255], v[146:147]
	v_lshlrev_b32_e32 v68, 16, v69
	v_and_b32_e32 v69, 0xffff0000, v69
	v_pk_fma_f32 v[150:151], v[58:59], v[68:69], v[150:151]
	s_waitcnt vmcnt(13)
	v_lshlrev_b32_e32 v254, 16, v70
	v_and_b32_e32 v255, 0xffff0000, v70
	v_pk_fma_f32 v[140:141], v[52:53], v[254:255], v[140:141]
	v_lshlrev_b32_e32 v70, 16, v71
	v_and_b32_e32 v71, 0xffff0000, v71
	v_pk_fma_f32 v[148:149], v[54:55], v[70:71], v[148:149]
	s_waitcnt vmcnt(12)
	v_lshlrev_b32_e32 v254, 16, v72
	v_and_b32_e32 v255, 0xffff0000, v72
	v_pk_fma_f32 v[138:139], v[48:49], v[254:255], v[138:139]
	v_lshlrev_b32_e32 v72, 16, v73
	v_and_b32_e32 v73, 0xffff0000, v73
	v_pk_fma_f32 v[142:143], v[50:51], v[72:73], v[142:143]
	s_waitcnt vmcnt(11)
	v_lshlrev_b32_e32 v254, 16, v74
	v_and_b32_e32 v255, 0xffff0000, v74
	v_pk_fma_f32 v[134:135], v[44:45], v[254:255], v[134:135]
	v_lshlrev_b32_e32 v74, 16, v75
	v_and_b32_e32 v75, 0xffff0000, v75
	v_pk_fma_f32 v[136:137], v[46:47], v[74:75], v[136:137]
	s_waitcnt vmcnt(10)
	v_lshlrev_b32_e32 v254, 16, v76
	v_and_b32_e32 v255, 0xffff0000, v76
	v_pk_fma_f32 v[130:131], v[40:41], v[254:255], v[130:131]
	v_lshlrev_b32_e32 v76, 16, v77
	v_and_b32_e32 v77, 0xffff0000, v77
	v_pk_fma_f32 v[132:133], v[42:43], v[76:77], v[132:133]
	s_waitcnt vmcnt(9)
	v_lshlrev_b32_e32 v254, 16, v78
	v_and_b32_e32 v255, 0xffff0000, v78
	v_pk_fma_f32 v[126:127], v[36:37], v[254:255], v[126:127]
	v_lshlrev_b32_e32 v78, 16, v79
	v_and_b32_e32 v79, 0xffff0000, v79
	v_pk_fma_f32 v[128:129], v[38:39], v[78:79], v[128:129]
	s_waitcnt vmcnt(8)
	v_lshlrev_b32_e32 v254, 16, v80
	v_and_b32_e32 v255, 0xffff0000, v80
	v_pk_fma_f32 v[122:123], v[32:33], v[254:255], v[122:123]
	v_lshlrev_b32_e32 v80, 16, v81
	v_and_b32_e32 v81, 0xffff0000, v81
	v_pk_fma_f32 v[124:125], v[34:35], v[80:81], v[124:125]
	s_waitcnt vmcnt(7)
	v_lshlrev_b32_e32 v254, 16, v82
	v_and_b32_e32 v255, 0xffff0000, v82
	v_pk_fma_f32 v[118:119], v[28:29], v[254:255], v[118:119]
	v_lshlrev_b32_e32 v82, 16, v83
	v_and_b32_e32 v83, 0xffff0000, v83
	v_pk_fma_f32 v[120:121], v[30:31], v[82:83], v[120:121]
	s_waitcnt vmcnt(6)
	v_lshlrev_b32_e32 v254, 16, v84
	v_and_b32_e32 v255, 0xffff0000, v84
	v_pk_fma_f32 v[114:115], v[24:25], v[254:255], v[114:115]
	v_lshlrev_b32_e32 v84, 16, v85
	v_and_b32_e32 v85, 0xffff0000, v85
	v_pk_fma_f32 v[116:117], v[26:27], v[84:85], v[116:117]
	s_waitcnt vmcnt(5)
	v_lshlrev_b32_e32 v254, 16, v86
	v_and_b32_e32 v255, 0xffff0000, v86
	v_pk_fma_f32 v[110:111], v[20:21], v[254:255], v[110:111]
	v_lshlrev_b32_e32 v86, 16, v87
	v_and_b32_e32 v87, 0xffff0000, v87
	v_pk_fma_f32 v[112:113], v[22:23], v[86:87], v[112:113]
	s_waitcnt vmcnt(4)
	v_lshlrev_b32_e32 v254, 16, v88
	v_and_b32_e32 v255, 0xffff0000, v88
	v_pk_fma_f32 v[106:107], v[16:17], v[254:255], v[106:107]
	v_lshlrev_b32_e32 v88, 16, v89
	v_and_b32_e32 v89, 0xffff0000, v89
	v_pk_fma_f32 v[108:109], v[18:19], v[88:89], v[108:109]
	s_waitcnt vmcnt(3)
	v_lshlrev_b32_e32 v254, 16, v200
	v_and_b32_e32 v255, 0xffff0000, v200
	v_pk_fma_f32 v[102:103], v[12:13], v[254:255], v[102:103]
	v_lshlrev_b32_e32 v200, 16, v201
	v_and_b32_e32 v201, 0xffff0000, v201
	v_pk_fma_f32 v[104:105], v[14:15], v[200:201], v[104:105]
	s_waitcnt vmcnt(2)
	v_lshlrev_b32_e32 v254, 16, v202
	v_and_b32_e32 v255, 0xffff0000, v202
	v_pk_fma_f32 v[98:99], v[8:9], v[254:255], v[98:99]
	v_lshlrev_b32_e32 v202, 16, v203
	v_and_b32_e32 v203, 0xffff0000, v203
	v_pk_fma_f32 v[100:101], v[10:11], v[202:203], v[100:101]
	s_waitcnt vmcnt(1)
	v_lshlrev_b32_e32 v254, 16, v204
	v_and_b32_e32 v255, 0xffff0000, v204
	v_pk_fma_f32 v[94:95], v[4:5], v[254:255], v[94:95]
	v_lshlrev_b32_e32 v204, 16, v205
	v_and_b32_e32 v205, 0xffff0000, v205
	v_pk_fma_f32 v[96:97], v[6:7], v[204:205], v[96:97]
	s_waitcnt vmcnt(0)
	v_lshlrev_b32_e32 v254, 16, v206
	v_and_b32_e32 v255, 0xffff0000, v206
	v_pk_fma_f32 v[90:91], v[0:1], v[254:255], v[90:91]
	v_lshlrev_b32_e32 v206, 16, v207
	v_and_b32_e32 v207, 0xffff0000, v207
	v_pk_fma_f32 v[92:93], v[2:3], v[206:207], v[92:93]
	s_add_i32 s1, s1, 1
	s_cmp_eq_u32 s1, 4
	s_cbranch_scc1 .LBB0_1171

.LBB0_1267:
	s_add_i32 s74, s74, 1
	s_lshl_b64 s[26:27], s[0:1], 20
	s_add_u32 s31, s40, s26
	s_addc_u32 s44, s41, s27
	s_lshl_b32 s0, s24, 8
	s_ashr_i32 s1, s0, 31
	s_lshl_b64 s[24:25], s[0:1], 2
	s_add_u32 s0, s31, s24
	s_mov_b32 s31, 0x3fff80
	s_addc_u32 s1, s44, s25
	s_add_u32 s26, s38, s26
	s_addc_u32 s27, s39, s27
	s_add_u32 s24, s26, s24
	s_addc_u32 s25, s27, s25
	v_lshrrev_b32_e32 v250, 1, v166
	v_and_b32_e32 v250, 0x80, v250
	v_and_b32_e32 v251, 15, v166
	v_or_b32_e32 v250, v250, v251
	v_lshrrev_b32_e32 v251, 2, v166
	v_and_b32_e32 v251, 12, v251
	v_and_b32_e32 v252, 0xc0, v166
	v_or_b32_e32 v251, v251, v252
	v_lshl_or_b32 v250, v250, 10, v251
	v_mov_b32_e32 v251, 0
	v_lshl_add_u64 v[246:247], v[250:251], 2, s[0:1]
	v_lshl_add_u64 v[248:249], v[250:251], 2, s[24:25]
	global_load_dwordx4 v[130:133], v[246:247], off
	global_load_dwordx4 v[134:137], v[246:247], off offset:64
	global_load_dwordx4 v[138:141], v[246:247], off offset:128
	global_load_dwordx4 v[142:145], v[246:247], off offset:192
	v_add_co_u32_e32 v246, vcc, 0x10000, v246
	s_nop 1
	v_addc_co_u32_e32 v247, vcc, 0, v247, vcc
	global_load_dwordx4 v[146:149], v[246:247], off
	global_load_dwordx4 v[150:153], v[246:247], off offset:64
	global_load_dwordx4 v[202:205], v[246:247], off offset:128
	global_load_dwordx4 v[206:209], v[246:247], off offset:192
	v_add_co_u32_e32 v246, vcc, 0x10000, v246
	s_nop 1
	v_addc_co_u32_e32 v247, vcc, 0, v247, vcc
	s_waitcnt vmcnt(4)
	v_pk_add_f32 v[126:127], v[126:127], v[130:131]
	v_pk_add_f32 v[128:129], v[128:129], v[132:133]
	v_pk_add_f32 v[122:123], v[122:123], v[134:135]
	v_pk_add_f32 v[124:125], v[124:125], v[136:137]
	v_pk_add_f32 v[118:119], v[118:119], v[138:139]
	v_pk_add_f32 v[120:121], v[120:121], v[140:141]
	v_pk_add_f32 v[114:115], v[114:115], v[142:143]
	v_pk_add_f32 v[116:117], v[116:117], v[144:145]
	global_store_dwordx4 v[248:249], v[126:129], off
	global_store_dwordx4 v[248:249], v[122:125], off offset:64
	global_store_dwordx4 v[248:249], v[118:121], off offset:128
	global_store_dwordx4 v[248:249], v[114:117], off offset:192
	v_add_co_u32_e32 v248, vcc, 0x10000, v248
	s_nop 1
	v_addc_co_u32_e32 v249, vcc, 0, v249, vcc
	global_load_dwordx4 v[130:133], v[246:247], off
	global_load_dwordx4 v[134:137], v[246:247], off offset:64
	global_load_dwordx4 v[138:141], v[246:247], off offset:128
	global_load_dwordx4 v[142:145], v[246:247], off offset:192
	v_add_co_u32_e32 v246, vcc, 0x10000, v246
	s_nop 1
	v_addc_co_u32_e32 v247, vcc, 0, v247, vcc
	global_load_dwordx4 v[126:129], v[246:247], off
	global_load_dwordx4 v[122:125], v[246:247], off offset:64
	global_load_dwordx4 v[118:121], v[246:247], off offset:128
	global_load_dwordx4 v[114:117], v[246:247], off offset:192
	v_add_co_u32_e32 v246, vcc, 0x10000, v246
	s_nop 1
	v_addc_co_u32_e32 v247, vcc, 0, v247, vcc
	s_waitcnt vmcnt(12)
	v_pk_add_f32 v[110:111], v[110:111], v[146:147]
	v_pk_add_f32 v[112:113], v[112:113], v[148:149]
	v_pk_add_f32 v[106:107], v[106:107], v[150:151]
	v_pk_add_f32 v[108:109], v[108:109], v[152:153]
	v_pk_add_f32 v[102:103], v[102:103], v[202:203]
	v_pk_add_f32 v[104:105], v[104:105], v[204:205]
	v_pk_add_f32 v[98:99], v[98:99], v[206:207]
	v_pk_add_f32 v[100:101], v[100:101], v[208:209]
	global_store_dwordx4 v[248:249], v[110:113], off
	global_store_dwordx4 v[248:249], v[106:109], off offset:64
	global_store_dwordx4 v[248:249], v[102:105], off offset:128
	global_store_dwordx4 v[248:249], v[98:101], off offset:192
	v_add_co_u32_e32 v248, vcc, 0x10000, v248
	s_nop 1
	v_addc_co_u32_e32 v249, vcc, 0, v249, vcc
	global_load_dwordx4 v[146:149], v[246:247], off
	global_load_dwordx4 v[150:153], v[246:247], off offset:64
	global_load_dwordx4 v[202:205], v[246:247], off offset:128
	global_load_dwordx4 v[206:209], v[246:247], off offset:192
	v_add_co_u32_e32 v246, vcc, 0x10000, v246
	s_nop 1
	v_addc_co_u32_e32 v247, vcc, 0, v247, vcc
	global_load_dwordx4 v[110:113], v[246:247], off
	global_load_dwordx4 v[106:109], v[246:247], off offset:64
	global_load_dwordx4 v[102:105], v[246:247], off offset:128
	global_load_dwordx4 v[98:101], v[246:247], off offset:192
	v_add_co_u32_e32 v246, vcc, 0x10000, v246
	s_nop 1
	v_addc_co_u32_e32 v247, vcc, 0, v247, vcc
	s_waitcnt vmcnt(16)
	v_pk_add_f32 v[94:95], v[94:95], v[130:131]
	v_pk_add_f32 v[96:97], v[96:97], v[132:133]
	v_pk_add_f32 v[90:91], v[90:91], v[134:135]
	v_pk_add_f32 v[92:93], v[92:93], v[136:137]
	v_pk_add_f32 v[86:87], v[86:87], v[138:139]
	v_pk_add_f32 v[88:89], v[88:89], v[140:141]
	v_pk_add_f32 v[82:83], v[82:83], v[142:143]
	v_pk_add_f32 v[84:85], v[84:85], v[144:145]
	global_store_dwordx4 v[248:249], v[94:97], off
	global_store_dwordx4 v[248:249], v[90:93], off offset:64
	global_store_dwordx4 v[248:249], v[86:89], off offset:128
	global_store_dwordx4 v[248:249], v[82:85], off offset:192
	v_add_co_u32_e32 v248, vcc, 0x10000, v248
	s_nop 1
	v_addc_co_u32_e32 v249, vcc, 0, v249, vcc
	global_load_dwordx4 v[130:133], v[246:247], off
	global_load_dwordx4 v[134:137], v[246:247], off offset:64
	global_load_dwordx4 v[138:141], v[246:247], off offset:128
	global_load_dwordx4 v[142:145], v[246:247], off offset:192
	v_add_co_u32_e32 v246, vcc, 0x10000, v246
	s_nop 1
	v_addc_co_u32_e32 v247, vcc, 0, v247, vcc
	global_load_dwordx4 v[94:97], v[246:247], off
	global_load_dwordx4 v[90:93], v[246:247], off offset:64
	global_load_dwordx4 v[86:89], v[246:247], off offset:128
	global_load_dwordx4 v[82:85], v[246:247], off offset:192
	s_waitcnt vmcnt(24)
	v_pk_add_f32 v[78:79], v[78:79], v[126:127]
	v_pk_add_f32 v[80:81], v[80:81], v[128:129]
	v_pk_add_f32 v[74:75], v[74:75], v[122:123]
	v_pk_add_f32 v[76:77], v[76:77], v[124:125]
	v_pk_add_f32 v[70:71], v[70:71], v[118:119]
	v_pk_add_f32 v[72:73], v[72:73], v[120:121]
	v_pk_add_f32 v[66:67], v[66:67], v[114:115]
	v_pk_add_f32 v[68:69], v[68:69], v[116:117]
	global_store_dwordx4 v[248:249], v[78:81], off
	global_store_dwordx4 v[248:249], v[74:77], off offset:64
	global_store_dwordx4 v[248:249], v[70:73], off offset:128
	global_store_dwordx4 v[248:249], v[66:69], off offset:192
	v_add_co_u32_e32 v248, vcc, 0x10000, v248
	s_nop 1
	v_addc_co_u32_e32 v249, vcc, 0, v249, vcc
	s_waitcnt vmcnt(20)
	v_pk_add_f32 v[60:61], v[60:61], v[146:147]
	v_pk_add_f32 v[62:63], v[62:63], v[148:149]
	v_pk_add_f32 v[56:57], v[56:57], v[150:151]
	v_pk_add_f32 v[58:59], v[58:59], v[152:153]
	v_pk_add_f32 v[52:53], v[52:53], v[202:203]
	v_pk_add_f32 v[54:55], v[54:55], v[204:205]
	v_pk_add_f32 v[48:49], v[48:49], v[206:207]
	v_pk_add_f32 v[50:51], v[50:51], v[208:209]
	global_store_dwordx4 v[248:249], v[60:63], off
	global_store_dwordx4 v[248:249], v[56:59], off offset:64
	global_store_dwordx4 v[248:249], v[52:55], off offset:128
	global_store_dwordx4 v[248:249], v[48:51], off offset:192
	v_add_co_u32_e32 v248, vcc, 0x10000, v248
	s_nop 1
	v_addc_co_u32_e32 v249, vcc, 0, v249, vcc
	s_waitcnt vmcnt(20)
	v_pk_add_f32 v[44:45], v[44:45], v[110:111]
	v_pk_add_f32 v[46:47], v[46:47], v[112:113]
	v_pk_add_f32 v[40:41], v[40:41], v[106:107]
	v_pk_add_f32 v[42:43], v[42:43], v[108:109]
	v_pk_add_f32 v[36:37], v[36:37], v[102:103]
	v_pk_add_f32 v[38:39], v[38:39], v[104:105]
	v_pk_add_f32 v[32:33], v[32:33], v[98:99]
	v_pk_add_f32 v[34:35], v[34:35], v[100:101]
	global_store_dwordx4 v[248:249], v[44:47], off
	global_store_dwordx4 v[248:249], v[40:43], off offset:64
	global_store_dwordx4 v[248:249], v[36:39], off offset:128
	global_store_dwordx4 v[248:249], v[32:35], off offset:192
	v_add_co_u32_e32 v248, vcc, 0x10000, v248
	s_nop 1
	v_addc_co_u32_e32 v249, vcc, 0, v249, vcc
	s_waitcnt vmcnt(16)
	v_pk_add_f32 v[28:29], v[28:29], v[130:131]
	v_pk_add_f32 v[30:31], v[30:31], v[132:133]
	v_pk_add_f32 v[24:25], v[24:25], v[134:135]
	v_pk_add_f32 v[26:27], v[26:27], v[136:137]
	v_pk_add_f32 v[20:21], v[20:21], v[138:139]
	v_pk_add_f32 v[22:23], v[22:23], v[140:141]
	v_pk_add_f32 v[16:17], v[16:17], v[142:143]
	v_pk_add_f32 v[18:19], v[18:19], v[144:145]
	global_store_dwordx4 v[248:249], v[28:31], off
	global_store_dwordx4 v[248:249], v[24:27], off offset:64
	global_store_dwordx4 v[248:249], v[20:23], off offset:128
	global_store_dwordx4 v[248:249], v[16:19], off offset:192
	v_add_co_u32_e32 v248, vcc, 0x10000, v248
	s_nop 1
	v_addc_co_u32_e32 v249, vcc, 0, v249, vcc
	s_waitcnt vmcnt(16)
	v_pk_add_f32 v[12:13], v[12:13], v[94:95]
	v_pk_add_f32 v[14:15], v[14:15], v[96:97]
	v_pk_add_f32 v[8:9], v[8:9], v[90:91]
	v_pk_add_f32 v[10:11], v[10:11], v[92:93]
	v_pk_add_f32 v[4:5], v[4:5], v[86:87]
	v_pk_add_f32 v[6:7], v[6:7], v[88:89]
	v_pk_add_f32 v[0:1], v[0:1], v[82:83]
	v_pk_add_f32 v[2:3], v[2:3], v[84:85]
	global_store_dwordx4 v[248:249], v[12:15], off
	global_store_dwordx4 v[248:249], v[8:11], off offset:64
	global_store_dwordx4 v[248:249], v[4:7], off offset:128
	global_store_dwordx4 v[248:249], v[0:3], off offset:192
	s_andn2_b64 vcc, exec, s[28:29]
	s_cbranch_vccz .LBB0_1297

.LBB0_1494:
	s_add_i32 s64, s64, 1
	s_lshl_b64 s[26:27], s[30:31], 20
	s_add_u32 s1, s38, s26
	s_addc_u32 s25, s39, s27
	s_lshl_b32 s26, s40, 8
	s_ashr_i32 s27, s26, 31
	s_lshl_b64 s[26:27], s[26:27], 2
	s_add_u32 s30, s1, s26
	s_mov_b32 s1, 0x3fff80
	s_addc_u32 s31, s25, s27
	v_lshrrev_b32_e32 v250, 1, v166
	v_and_b32_e32 v250, 0x80, v250
	v_and_b32_e32 v251, 15, v166
	v_or_b32_e32 v250, v250, v251
	v_lshrrev_b32_e32 v251, 2, v166
	v_and_b32_e32 v251, 12, v251
	v_and_b32_e32 v252, 0xc0, v166
	v_or_b32_e32 v251, v251, v252
	v_lshl_or_b32 v250, v250, 10, v251
	v_mov_b32_e32 v251, 0
	v_lshl_add_u64 v[246:247], v[250:251], 2, s[30:31]
	v_mov_b32_e32 v248, v246
	v_mov_b32_e32 v249, v247
	global_load_dwordx4 v[130:133], v[246:247], off
	global_load_dwordx4 v[134:137], v[246:247], off offset:64
	global_load_dwordx4 v[138:141], v[246:247], off offset:128
	global_load_dwordx4 v[142:145], v[246:247], off offset:192
	v_add_co_u32_e32 v246, vcc, 0x10000, v246
	s_nop 1
	v_addc_co_u32_e32 v247, vcc, 0, v247, vcc
	global_load_dwordx4 v[146:149], v[246:247], off
	global_load_dwordx4 v[150:153], v[246:247], off offset:64
	global_load_dwordx4 v[202:205], v[246:247], off offset:128
	global_load_dwordx4 v[206:209], v[246:247], off offset:192
	v_add_co_u32_e32 v246, vcc, 0x10000, v246
	s_nop 1
	v_addc_co_u32_e32 v247, vcc, 0, v247, vcc
	s_waitcnt vmcnt(4)
	v_pk_add_f32 v[126:127], v[126:127], v[130:131]
	v_pk_add_f32 v[128:129], v[128:129], v[132:133]
	v_pk_add_f32 v[122:123], v[122:123], v[134:135]
	v_pk_add_f32 v[124:125], v[124:125], v[136:137]
	v_pk_add_f32 v[118:119], v[118:119], v[138:139]
	v_pk_add_f32 v[120:121], v[120:121], v[140:141]
	v_pk_add_f32 v[114:115], v[114:115], v[142:143]
	v_pk_add_f32 v[116:117], v[116:117], v[144:145]
	global_store_dwordx4 v[248:249], v[126:129], off
	global_store_dwordx4 v[248:249], v[122:125], off offset:64
	global_store_dwordx4 v[248:249], v[118:121], off offset:128
	global_store_dwordx4 v[248:249], v[114:117], off offset:192
	v_add_co_u32_e32 v248, vcc, 0x10000, v248
	s_nop 1
	v_addc_co_u32_e32 v249, vcc, 0, v249, vcc
	global_load_dwordx4 v[130:133], v[246:247], off
	global_load_dwordx4 v[134:137], v[246:247], off offset:64
	global_load_dwordx4 v[138:141], v[246:247], off offset:128
	global_load_dwordx4 v[142:145], v[246:247], off offset:192
	v_add_co_u32_e32 v246, vcc, 0x10000, v246
	s_nop 1
	v_addc_co_u32_e32 v247, vcc, 0, v247, vcc
	global_load_dwordx4 v[126:129], v[246:247], off
	global_load_dwordx4 v[122:125], v[246:247], off offset:64
	global_load_dwordx4 v[118:121], v[246:247], off offset:128
	global_load_dwordx4 v[114:117], v[246:247], off offset:192
	v_add_co_u32_e32 v246, vcc, 0x10000, v246
	s_nop 1
	v_addc_co_u32_e32 v247, vcc, 0, v247, vcc
	s_waitcnt vmcnt(12)
	v_pk_add_f32 v[110:111], v[110:111], v[146:147]
	v_pk_add_f32 v[112:113], v[112:113], v[148:149]
	v_pk_add_f32 v[106:107], v[106:107], v[150:151]
	v_pk_add_f32 v[108:109], v[108:109], v[152:153]
	v_pk_add_f32 v[102:103], v[102:103], v[202:203]
	v_pk_add_f32 v[104:105], v[104:105], v[204:205]
	v_pk_add_f32 v[98:99], v[98:99], v[206:207]
	v_pk_add_f32 v[100:101], v[100:101], v[208:209]
	global_store_dwordx4 v[248:249], v[110:113], off
	global_store_dwordx4 v[248:249], v[106:109], off offset:64
	global_store_dwordx4 v[248:249], v[102:105], off offset:128
	global_store_dwordx4 v[248:249], v[98:101], off offset:192
	v_add_co_u32_e32 v248, vcc, 0x10000, v248
	s_nop 1
	v_addc_co_u32_e32 v249, vcc, 0, v249, vcc
	global_load_dwordx4 v[146:149], v[246:247], off
	global_load_dwordx4 v[150:153], v[246:247], off offset:64
	global_load_dwordx4 v[202:205], v[246:247], off offset:128
	global_load_dwordx4 v[206:209], v[246:247], off offset:192
	v_add_co_u32_e32 v246, vcc, 0x10000, v246
	s_nop 1
	v_addc_co_u32_e32 v247, vcc, 0, v247, vcc
	global_load_dwordx4 v[110:113], v[246:247], off
	global_load_dwordx4 v[106:109], v[246:247], off offset:64
	global_load_dwordx4 v[102:105], v[246:247], off offset:128
	global_load_dwordx4 v[98:101], v[246:247], off offset:192
	v_add_co_u32_e32 v246, vcc, 0x10000, v246
	s_nop 1
	v_addc_co_u32_e32 v247, vcc, 0, v247, vcc
	s_waitcnt vmcnt(16)
	v_pk_add_f32 v[94:95], v[94:95], v[130:131]
	v_pk_add_f32 v[96:97], v[96:97], v[132:133]
	v_pk_add_f32 v[90:91], v[90:91], v[134:135]
	v_pk_add_f32 v[92:93], v[92:93], v[136:137]
	v_pk_add_f32 v[86:87], v[86:87], v[138:139]
	v_pk_add_f32 v[88:89], v[88:89], v[140:141]
	v_pk_add_f32 v[82:83], v[82:83], v[142:143]
	v_pk_add_f32 v[84:85], v[84:85], v[144:145]
	global_store_dwordx4 v[248:249], v[94:97], off
	global_store_dwordx4 v[248:249], v[90:93], off offset:64
	global_store_dwordx4 v[248:249], v[86:89], off offset:128
	global_store_dwordx4 v[248:249], v[82:85], off offset:192
	v_add_co_u32_e32 v248, vcc, 0x10000, v248
	s_nop 1
	v_addc_co_u32_e32 v249, vcc, 0, v249, vcc
	global_load_dwordx4 v[130:133], v[246:247], off
	global_load_dwordx4 v[134:137], v[246:247], off offset:64
	global_load_dwordx4 v[138:141], v[246:247], off offset:128
	global_load_dwordx4 v[142:145], v[246:247], off offset:192
	v_add_co_u32_e32 v246, vcc, 0x10000, v246
	s_nop 1
	v_addc_co_u32_e32 v247, vcc, 0, v247, vcc
	global_load_dwordx4 v[94:97], v[246:247], off
	global_load_dwordx4 v[90:93], v[246:247], off offset:64
	global_load_dwordx4 v[86:89], v[246:247], off offset:128
	global_load_dwordx4 v[82:85], v[246:247], off offset:192
	s_waitcnt vmcnt(24)
	v_pk_add_f32 v[78:79], v[78:79], v[126:127]
	v_pk_add_f32 v[80:81], v[80:81], v[128:129]
	v_pk_add_f32 v[74:75], v[74:75], v[122:123]
	v_pk_add_f32 v[76:77], v[76:77], v[124:125]
	v_pk_add_f32 v[70:71], v[70:71], v[118:119]
	v_pk_add_f32 v[72:73], v[72:73], v[120:121]
	v_pk_add_f32 v[66:67], v[66:67], v[114:115]
	v_pk_add_f32 v[68:69], v[68:69], v[116:117]
	global_store_dwordx4 v[248:249], v[78:81], off
	global_store_dwordx4 v[248:249], v[74:77], off offset:64
	global_store_dwordx4 v[248:249], v[70:73], off offset:128
	global_store_dwordx4 v[248:249], v[66:69], off offset:192
	v_add_co_u32_e32 v248, vcc, 0x10000, v248
	s_nop 1
	v_addc_co_u32_e32 v249, vcc, 0, v249, vcc
	s_waitcnt vmcnt(20)
	v_pk_add_f32 v[60:61], v[60:61], v[146:147]
	v_pk_add_f32 v[62:63], v[62:63], v[148:149]
	v_pk_add_f32 v[56:57], v[56:57], v[150:151]
	v_pk_add_f32 v[58:59], v[58:59], v[152:153]
	v_pk_add_f32 v[52:53], v[52:53], v[202:203]
	v_pk_add_f32 v[54:55], v[54:55], v[204:205]
	v_pk_add_f32 v[48:49], v[48:49], v[206:207]
	v_pk_add_f32 v[50:51], v[50:51], v[208:209]
	global_store_dwordx4 v[248:249], v[60:63], off
	global_store_dwordx4 v[248:249], v[56:59], off offset:64
	global_store_dwordx4 v[248:249], v[52:55], off offset:128
	global_store_dwordx4 v[248:249], v[48:51], off offset:192
	v_add_co_u32_e32 v248, vcc, 0x10000, v248
	s_nop 1
	v_addc_co_u32_e32 v249, vcc, 0, v249, vcc
	s_waitcnt vmcnt(20)
	v_pk_add_f32 v[44:45], v[44:45], v[110:111]
	v_pk_add_f32 v[46:47], v[46:47], v[112:113]
	v_pk_add_f32 v[40:41], v[40:41], v[106:107]
	v_pk_add_f32 v[42:43], v[42:43], v[108:109]
	v_pk_add_f32 v[36:37], v[36:37], v[102:103]
	v_pk_add_f32 v[38:39], v[38:39], v[104:105]
	v_pk_add_f32 v[32:33], v[32:33], v[98:99]
	v_pk_add_f32 v[34:35], v[34:35], v[100:101]
	global_store_dwordx4 v[248:249], v[44:47], off
	global_store_dwordx4 v[248:249], v[40:43], off offset:64
	global_store_dwordx4 v[248:249], v[36:39], off offset:128
	global_store_dwordx4 v[248:249], v[32:35], off offset:192
	v_add_co_u32_e32 v248, vcc, 0x10000, v248
	s_nop 1
	v_addc_co_u32_e32 v249, vcc, 0, v249, vcc
	s_waitcnt vmcnt(16)
	v_pk_add_f32 v[28:29], v[28:29], v[130:131]
	v_pk_add_f32 v[30:31], v[30:31], v[132:133]
	v_pk_add_f32 v[24:25], v[24:25], v[134:135]
	v_pk_add_f32 v[26:27], v[26:27], v[136:137]
	v_pk_add_f32 v[20:21], v[20:21], v[138:139]
	v_pk_add_f32 v[22:23], v[22:23], v[140:141]
	v_pk_add_f32 v[16:17], v[16:17], v[142:143]
	v_pk_add_f32 v[18:19], v[18:19], v[144:145]
	global_store_dwordx4 v[248:249], v[28:31], off
	global_store_dwordx4 v[248:249], v[24:27], off offset:64
	global_store_dwordx4 v[248:249], v[20:23], off offset:128
	global_store_dwordx4 v[248:249], v[16:19], off offset:192
	v_add_co_u32_e32 v248, vcc, 0x10000, v248
	s_nop 1
	v_addc_co_u32_e32 v249, vcc, 0, v249, vcc
	s_waitcnt vmcnt(16)
	v_pk_add_f32 v[12:13], v[12:13], v[94:95]
	v_pk_add_f32 v[14:15], v[14:15], v[96:97]
	v_pk_add_f32 v[8:9], v[8:9], v[90:91]
	v_pk_add_f32 v[10:11], v[10:11], v[92:93]
	v_pk_add_f32 v[4:5], v[4:5], v[86:87]
	v_pk_add_f32 v[6:7], v[6:7], v[88:89]
	v_pk_add_f32 v[0:1], v[0:1], v[82:83]
	v_pk_add_f32 v[2:3], v[2:3], v[84:85]
	global_store_dwordx4 v[248:249], v[12:15], off
	global_store_dwordx4 v[248:249], v[8:11], off offset:64
	global_store_dwordx4 v[248:249], v[4:7], off offset:128
	global_store_dwordx4 v[248:249], v[0:3], off offset:192
	s_andn2_b64 vcc, exec, s[28:29]
	s_cbranch_vccz .LBB0_1524

.LBB0_1782:
	s_add_i32 s40, s40, 1
	s_lshl_b64 s[24:25], s[24:25], 20
	s_add_u32 s26, s38, s24
	s_addc_u32 s27, s39, s25
	s_lshl_b32 s24, s44, 8
	s_ashr_i32 s25, s24, 31
	s_lshl_b64 s[24:25], s[24:25], 2
	s_add_u32 s24, s26, s24
	s_mov_b32 s26, 0x3fff80
	s_addc_u32 s25, s27, s25
	v_lshrrev_b32_e32 v250, 1, v166
	v_and_b32_e32 v250, 0x80, v250
	v_and_b32_e32 v251, 15, v166
	v_or_b32_e32 v250, v250, v251
	v_lshrrev_b32_e32 v251, 2, v166
	v_and_b32_e32 v251, 12, v251
	v_and_b32_e32 v252, 0xc0, v166
	v_or_b32_e32 v251, v251, v252
	v_lshl_or_b32 v250, v250, 10, v251
	v_mov_b32_e32 v251, 0
	v_lshl_add_u64 v[246:247], v[250:251], 2, s[24:25]
	v_mov_b32_e32 v248, v246
	v_mov_b32_e32 v249, v247
	global_load_dwordx4 v[130:133], v[246:247], off
	global_load_dwordx4 v[134:137], v[246:247], off offset:64
	global_load_dwordx4 v[138:141], v[246:247], off offset:128
	global_load_dwordx4 v[142:145], v[246:247], off offset:192
	v_add_co_u32_e32 v246, vcc, 0x10000, v246
	s_nop 1
	v_addc_co_u32_e32 v247, vcc, 0, v247, vcc
	global_load_dwordx4 v[146:149], v[246:247], off
	global_load_dwordx4 v[150:153], v[246:247], off offset:64
	global_load_dwordx4 v[202:205], v[246:247], off offset:128
	global_load_dwordx4 v[206:209], v[246:247], off offset:192
	v_add_co_u32_e32 v246, vcc, 0x10000, v246
	s_nop 1
	v_addc_co_u32_e32 v247, vcc, 0, v247, vcc
	s_waitcnt vmcnt(4)
	v_pk_add_f32 v[126:127], v[126:127], v[130:131]
	v_pk_add_f32 v[128:129], v[128:129], v[132:133]
	v_pk_add_f32 v[122:123], v[122:123], v[134:135]
	v_pk_add_f32 v[124:125], v[124:125], v[136:137]
	v_pk_add_f32 v[118:119], v[118:119], v[138:139]
	v_pk_add_f32 v[120:121], v[120:121], v[140:141]
	v_pk_add_f32 v[114:115], v[114:115], v[142:143]
	v_pk_add_f32 v[116:117], v[116:117], v[144:145]
	global_store_dwordx4 v[248:249], v[126:129], off
	global_store_dwordx4 v[248:249], v[122:125], off offset:64
	global_store_dwordx4 v[248:249], v[118:121], off offset:128
	global_store_dwordx4 v[248:249], v[114:117], off offset:192
	v_add_co_u32_e32 v248, vcc, 0x10000, v248
	s_nop 1
	v_addc_co_u32_e32 v249, vcc, 0, v249, vcc
	global_load_dwordx4 v[130:133], v[246:247], off
	global_load_dwordx4 v[134:137], v[246:247], off offset:64
	global_load_dwordx4 v[138:141], v[246:247], off offset:128
	global_load_dwordx4 v[142:145], v[246:247], off offset:192
	v_add_co_u32_e32 v246, vcc, 0x10000, v246
	s_nop 1
	v_addc_co_u32_e32 v247, vcc, 0, v247, vcc
	global_load_dwordx4 v[126:129], v[246:247], off
	global_load_dwordx4 v[122:125], v[246:247], off offset:64
	global_load_dwordx4 v[118:121], v[246:247], off offset:128
	global_load_dwordx4 v[114:117], v[246:247], off offset:192
	v_add_co_u32_e32 v246, vcc, 0x10000, v246
	s_nop 1
	v_addc_co_u32_e32 v247, vcc, 0, v247, vcc
	s_waitcnt vmcnt(12)
	v_pk_add_f32 v[110:111], v[110:111], v[146:147]
	v_pk_add_f32 v[112:113], v[112:113], v[148:149]
	v_pk_add_f32 v[106:107], v[106:107], v[150:151]
	v_pk_add_f32 v[108:109], v[108:109], v[152:153]
	v_pk_add_f32 v[102:103], v[102:103], v[202:203]
	v_pk_add_f32 v[104:105], v[104:105], v[204:205]
	v_pk_add_f32 v[98:99], v[98:99], v[206:207]
	v_pk_add_f32 v[100:101], v[100:101], v[208:209]
	global_store_dwordx4 v[248:249], v[110:113], off
	global_store_dwordx4 v[248:249], v[106:109], off offset:64
	global_store_dwordx4 v[248:249], v[102:105], off offset:128
	global_store_dwordx4 v[248:249], v[98:101], off offset:192
	v_add_co_u32_e32 v248, vcc, 0x10000, v248
	s_nop 1
	v_addc_co_u32_e32 v249, vcc, 0, v249, vcc
	global_load_dwordx4 v[146:149], v[246:247], off
	global_load_dwordx4 v[150:153], v[246:247], off offset:64
	global_load_dwordx4 v[202:205], v[246:247], off offset:128
	global_load_dwordx4 v[206:209], v[246:247], off offset:192
	v_add_co_u32_e32 v246, vcc, 0x10000, v246
	s_nop 1
	v_addc_co_u32_e32 v247, vcc, 0, v247, vcc
	global_load_dwordx4 v[110:113], v[246:247], off
	global_load_dwordx4 v[106:109], v[246:247], off offset:64
	global_load_dwordx4 v[102:105], v[246:247], off offset:128
	global_load_dwordx4 v[98:101], v[246:247], off offset:192
	v_add_co_u32_e32 v246, vcc, 0x10000, v246
	s_nop 1
	v_addc_co_u32_e32 v247, vcc, 0, v247, vcc
	s_waitcnt vmcnt(16)
	v_pk_add_f32 v[94:95], v[94:95], v[130:131]
	v_pk_add_f32 v[96:97], v[96:97], v[132:133]
	v_pk_add_f32 v[90:91], v[90:91], v[134:135]
	v_pk_add_f32 v[92:93], v[92:93], v[136:137]
	v_pk_add_f32 v[86:87], v[86:87], v[138:139]
	v_pk_add_f32 v[88:89], v[88:89], v[140:141]
	v_pk_add_f32 v[82:83], v[82:83], v[142:143]
	v_pk_add_f32 v[84:85], v[84:85], v[144:145]
	global_store_dwordx4 v[248:249], v[94:97], off
	global_store_dwordx4 v[248:249], v[90:93], off offset:64
	global_store_dwordx4 v[248:249], v[86:89], off offset:128
	global_store_dwordx4 v[248:249], v[82:85], off offset:192
	v_add_co_u32_e32 v248, vcc, 0x10000, v248
	s_nop 1
	v_addc_co_u32_e32 v249, vcc, 0, v249, vcc
	global_load_dwordx4 v[130:133], v[246:247], off
	global_load_dwordx4 v[134:137], v[246:247], off offset:64
	global_load_dwordx4 v[138:141], v[246:247], off offset:128
	global_load_dwordx4 v[142:145], v[246:247], off offset:192
	v_add_co_u32_e32 v246, vcc, 0x10000, v246
	s_nop 1
	v_addc_co_u32_e32 v247, vcc, 0, v247, vcc
	global_load_dwordx4 v[94:97], v[246:247], off
	global_load_dwordx4 v[90:93], v[246:247], off offset:64
	global_load_dwordx4 v[86:89], v[246:247], off offset:128
	global_load_dwordx4 v[82:85], v[246:247], off offset:192
	s_waitcnt vmcnt(24)
	v_pk_add_f32 v[78:79], v[78:79], v[126:127]
	v_pk_add_f32 v[80:81], v[80:81], v[128:129]
	v_pk_add_f32 v[74:75], v[74:75], v[122:123]
	v_pk_add_f32 v[76:77], v[76:77], v[124:125]
	v_pk_add_f32 v[70:71], v[70:71], v[118:119]
	v_pk_add_f32 v[72:73], v[72:73], v[120:121]
	v_pk_add_f32 v[66:67], v[66:67], v[114:115]
	v_pk_add_f32 v[68:69], v[68:69], v[116:117]
	global_store_dwordx4 v[248:249], v[78:81], off
	global_store_dwordx4 v[248:249], v[74:77], off offset:64
	global_store_dwordx4 v[248:249], v[70:73], off offset:128
	global_store_dwordx4 v[248:249], v[66:69], off offset:192
	v_add_co_u32_e32 v248, vcc, 0x10000, v248
	s_nop 1
	v_addc_co_u32_e32 v249, vcc, 0, v249, vcc
	s_waitcnt vmcnt(20)
	v_pk_add_f32 v[60:61], v[60:61], v[146:147]
	v_pk_add_f32 v[62:63], v[62:63], v[148:149]
	v_pk_add_f32 v[56:57], v[56:57], v[150:151]
	v_pk_add_f32 v[58:59], v[58:59], v[152:153]
	v_pk_add_f32 v[52:53], v[52:53], v[202:203]
	v_pk_add_f32 v[54:55], v[54:55], v[204:205]
	v_pk_add_f32 v[48:49], v[48:49], v[206:207]
	v_pk_add_f32 v[50:51], v[50:51], v[208:209]
	global_store_dwordx4 v[248:249], v[60:63], off
	global_store_dwordx4 v[248:249], v[56:59], off offset:64
	global_store_dwordx4 v[248:249], v[52:55], off offset:128
	global_store_dwordx4 v[248:249], v[48:51], off offset:192
	v_add_co_u32_e32 v248, vcc, 0x10000, v248
	s_nop 1
	v_addc_co_u32_e32 v249, vcc, 0, v249, vcc
	s_waitcnt vmcnt(20)
	v_pk_add_f32 v[44:45], v[44:45], v[110:111]
	v_pk_add_f32 v[46:47], v[46:47], v[112:113]
	v_pk_add_f32 v[40:41], v[40:41], v[106:107]
	v_pk_add_f32 v[42:43], v[42:43], v[108:109]
	v_pk_add_f32 v[36:37], v[36:37], v[102:103]
	v_pk_add_f32 v[38:39], v[38:39], v[104:105]
	v_pk_add_f32 v[32:33], v[32:33], v[98:99]
	v_pk_add_f32 v[34:35], v[34:35], v[100:101]
	global_store_dwordx4 v[248:249], v[44:47], off
	global_store_dwordx4 v[248:249], v[40:43], off offset:64
	global_store_dwordx4 v[248:249], v[36:39], off offset:128
	global_store_dwordx4 v[248:249], v[32:35], off offset:192
	v_add_co_u32_e32 v248, vcc, 0x10000, v248
	s_nop 1
	v_addc_co_u32_e32 v249, vcc, 0, v249, vcc
	s_waitcnt vmcnt(16)
	v_pk_add_f32 v[28:29], v[28:29], v[130:131]
	v_pk_add_f32 v[30:31], v[30:31], v[132:133]
	v_pk_add_f32 v[24:25], v[24:25], v[134:135]
	v_pk_add_f32 v[26:27], v[26:27], v[136:137]
	v_pk_add_f32 v[20:21], v[20:21], v[138:139]
	v_pk_add_f32 v[22:23], v[22:23], v[140:141]
	v_pk_add_f32 v[16:17], v[16:17], v[142:143]
	v_pk_add_f32 v[18:19], v[18:19], v[144:145]
	global_store_dwordx4 v[248:249], v[28:31], off
	global_store_dwordx4 v[248:249], v[24:27], off offset:64
	global_store_dwordx4 v[248:249], v[20:23], off offset:128
	global_store_dwordx4 v[248:249], v[16:19], off offset:192
	v_add_co_u32_e32 v248, vcc, 0x10000, v248
	s_nop 1
	v_addc_co_u32_e32 v249, vcc, 0, v249, vcc
	s_waitcnt vmcnt(16)
	v_pk_add_f32 v[12:13], v[12:13], v[94:95]
	v_pk_add_f32 v[14:15], v[14:15], v[96:97]
	v_pk_add_f32 v[8:9], v[8:9], v[90:91]
	v_pk_add_f32 v[10:11], v[10:11], v[92:93]
	v_pk_add_f32 v[4:5], v[4:5], v[86:87]
	v_pk_add_f32 v[6:7], v[6:7], v[88:89]
	v_pk_add_f32 v[0:1], v[0:1], v[82:83]
	v_pk_add_f32 v[2:3], v[2:3], v[84:85]
	global_store_dwordx4 v[248:249], v[12:15], off
	global_store_dwordx4 v[248:249], v[8:11], off offset:64
	global_store_dwordx4 v[248:249], v[4:7], off offset:128
	global_store_dwordx4 v[248:249], v[0:3], off offset:192
	s_andn2_b64 vcc, exec, s[0:1]
	s_cbranch_vccz .LBB0_502
